# fused final-norm epilogue (P8) hand-written: base loads in a ring, one panel sync, gains and row sums loaded once, 32 stores back to back
# baseline (speedup 1.0000x reference)
.LBB0_1043:
	v_lshl_add_u32 v209, s45, 8, v168
	v_lshl_or_b32 v204, s46, 8, v170
	v_lshl_add_u32 v203, v209, 11, v204
	v_lshlrev_b32_e32 v202, 1, v203
	v_lshlrev_b32_e32 v203, 1, v203
	v_lshlrev_b32_e32 v205, 2, v209
	v_mov_b32_e32 v204, v202
	global_load_dwordx2 v[140:141], v204, s[18:19]
	global_load_dwordx2 v[142:143], v204, s[18:19] offset:32
	global_load_dwordx2 v[144:145], v204, s[18:19] offset:256
	global_load_dwordx2 v[146:147], v204, s[18:19] offset:288
	v_add_u32_e32 v204, 0x10000, v202
	global_load_dwordx2 v[148:149], v204, s[18:19]
	global_load_dwordx2 v[150:151], v204, s[18:19] offset:32
	global_load_dwordx2 v[152:153], v204, s[18:19] offset:256
	global_load_dwordx2 v[154:155], v204, s[18:19] offset:288
	v_add_u32_e32 v204, 0x20000, v202
	global_load_dwordx2 v[156:157], v204, s[18:19]
	global_load_dwordx2 v[158:159], v204, s[18:19] offset:32
	global_load_dwordx2 v[160:161], v204, s[18:19] offset:256
	global_load_dwordx2 v[162:163], v204, s[18:19] offset:288
	v_add_u32_e32 v204, 0x30000, v202
	global_load_dwordx2 v[164:165], v204, s[18:19]
	global_load_dwordx2 v[176:177], v204, s[18:19] offset:32
	global_load_dwordx2 v[180:181], v204, s[18:19] offset:256
	global_load_dwordx2 v[182:183], v204, s[18:19] offset:288
	v_add_u32_e32 v204, 0x80000, v202
	global_load_dwordx2 v[184:185], v204, s[18:19]
	global_load_dwordx2 v[186:187], v204, s[18:19] offset:32
	global_load_dwordx2 v[188:189], v204, s[18:19] offset:256
	global_load_dwordx2 v[190:191], v204, s[18:19] offset:288
	v_mbcnt_lo_u32_b32 v206, -1, 0
	v_mbcnt_hi_u32_b32 v206, -1, v206
	v_xor_b32_e32 v207, 16, v206
	v_xor_b32_e32 v208, 32, v206
	v_lshlrev_b32_e32 v207, 2, v207
	v_lshlrev_b32_e32 v208, 2, v208
	s_waitcnt vmcnt(16)
	v_lshlrev_b32_e32 v192, 16, v140
	v_and_b32_e32 v193, 0xffff0000, v140
	v_lshlrev_b32_e32 v194, 16, v141
	v_and_b32_e32 v195, 0xffff0000, v141
	v_pk_fma_f32 v[124:125], v[124:125], 0.5, v[192:193] op_sel_hi:[1,0,1]
	v_pk_fma_f32 v[126:127], v[126:127], 0.5, v[194:195] op_sel_hi:[1,0,1]
	v_lshlrev_b32_e32 v192, 16, v142
	v_and_b32_e32 v193, 0xffff0000, v142
	v_lshlrev_b32_e32 v194, 16, v143
	v_and_b32_e32 v195, 0xffff0000, v143
	v_pk_fma_f32 v[120:121], v[120:121], 0.5, v[192:193] op_sel_hi:[1,0,1]
	v_pk_fma_f32 v[122:123], v[122:123], 0.5, v[194:195] op_sel_hi:[1,0,1]
	v_lshlrev_b32_e32 v192, 16, v144
	v_and_b32_e32 v193, 0xffff0000, v144
	v_lshlrev_b32_e32 v194, 16, v145
	v_and_b32_e32 v195, 0xffff0000, v145
	v_pk_fma_f32 v[116:117], v[116:117], 0.5, v[192:193] op_sel_hi:[1,0,1]
	v_pk_fma_f32 v[118:119], v[118:119], 0.5, v[194:195] op_sel_hi:[1,0,1]
	v_lshlrev_b32_e32 v192, 16, v146
	v_and_b32_e32 v193, 0xffff0000, v146
	v_lshlrev_b32_e32 v194, 16, v147
	v_and_b32_e32 v195, 0xffff0000, v147
	v_pk_fma_f32 v[112:113], v[112:113], 0.5, v[192:193] op_sel_hi:[1,0,1]
	v_pk_fma_f32 v[114:115], v[114:115], 0.5, v[194:195] op_sel_hi:[1,0,1]
	v_mul_f32_e32 v140, v125, v125
	v_mul_f32_e32 v142, v121, v121
	v_mul_f32_e32 v144, v117, v117
	v_mul_f32_e32 v146, v113, v113
	v_mul_f32_e32 v141, v127, v127
	v_mul_f32_e32 v143, v123, v123
	v_mul_f32_e32 v145, v119, v119
	v_mul_f32_e32 v147, v115, v115
	v_fmac_f32_e32 v140, v124, v124
	v_fmac_f32_e32 v142, v120, v120
	v_fmac_f32_e32 v144, v116, v116
	v_fmac_f32_e32 v146, v112, v112
	v_fmac_f32_e32 v141, v126, v126
	v_fmac_f32_e32 v143, v122, v122
	v_fmac_f32_e32 v145, v118, v118
	v_fmac_f32_e32 v147, v114, v114
	v_add_f32_e32 v140, v140, v141
	v_add_f32_e32 v142, v142, v143
	v_add_f32_e32 v144, v144, v145
	v_add_f32_e32 v146, v146, v147
	v_add_f32_e32 v167, v140, v142
	v_add_f32_e32 v167, v167, v144
	v_add_f32_e32 v167, v167, v146
	v_add_u32_e32 v204, 0x90000, v202
	global_load_dwordx2 v[140:141], v204, s[18:19]
	global_load_dwordx2 v[142:143], v204, s[18:19] offset:32
	global_load_dwordx2 v[144:145], v204, s[18:19] offset:256
	global_load_dwordx2 v[146:147], v204, s[18:19] offset:288
	s_waitcnt vmcnt(16)
	v_lshlrev_b32_e32 v192, 16, v148
	v_and_b32_e32 v193, 0xffff0000, v148
	v_lshlrev_b32_e32 v194, 16, v149
	v_and_b32_e32 v195, 0xffff0000, v149
	v_pk_fma_f32 v[108:109], v[108:109], 0.5, v[192:193] op_sel_hi:[1,0,1]
	v_pk_fma_f32 v[110:111], v[110:111], 0.5, v[194:195] op_sel_hi:[1,0,1]
	v_lshlrev_b32_e32 v192, 16, v150
	v_and_b32_e32 v193, 0xffff0000, v150
	v_lshlrev_b32_e32 v194, 16, v151
	v_and_b32_e32 v195, 0xffff0000, v151
	v_pk_fma_f32 v[104:105], v[104:105], 0.5, v[192:193] op_sel_hi:[1,0,1]
	v_pk_fma_f32 v[106:107], v[106:107], 0.5, v[194:195] op_sel_hi:[1,0,1]
	v_lshlrev_b32_e32 v192, 16, v152
	v_and_b32_e32 v193, 0xffff0000, v152
	v_lshlrev_b32_e32 v194, 16, v153
	v_and_b32_e32 v195, 0xffff0000, v153
	v_pk_fma_f32 v[100:101], v[100:101], 0.5, v[192:193] op_sel_hi:[1,0,1]
	v_pk_fma_f32 v[102:103], v[102:103], 0.5, v[194:195] op_sel_hi:[1,0,1]
	v_lshlrev_b32_e32 v192, 16, v154
	v_and_b32_e32 v193, 0xffff0000, v154
	v_lshlrev_b32_e32 v194, 16, v155
	v_and_b32_e32 v195, 0xffff0000, v155
	v_pk_fma_f32 v[96:97], v[96:97], 0.5, v[192:193] op_sel_hi:[1,0,1]
	v_pk_fma_f32 v[98:99], v[98:99], 0.5, v[194:195] op_sel_hi:[1,0,1]
	v_mul_f32_e32 v148, v109, v109
	v_mul_f32_e32 v150, v105, v105
	v_mul_f32_e32 v152, v101, v101
	v_mul_f32_e32 v154, v97, v97
	v_mul_f32_e32 v149, v111, v111
	v_mul_f32_e32 v151, v107, v107
	v_mul_f32_e32 v153, v103, v103
	v_mul_f32_e32 v155, v99, v99
	v_fmac_f32_e32 v148, v108, v108
	v_fmac_f32_e32 v150, v104, v104
	v_fmac_f32_e32 v152, v100, v100
	v_fmac_f32_e32 v154, v96, v96
	v_fmac_f32_e32 v149, v110, v110
	v_fmac_f32_e32 v151, v106, v106
	v_fmac_f32_e32 v153, v102, v102
	v_fmac_f32_e32 v155, v98, v98
	v_add_f32_e32 v148, v148, v149
	v_add_f32_e32 v150, v150, v151
	v_add_f32_e32 v152, v152, v153
	v_add_f32_e32 v154, v154, v155
	v_add_f32_e32 v175, v148, v150
	v_add_f32_e32 v175, v175, v152
	v_add_f32_e32 v175, v175, v154
	v_add_u32_e32 v204, 0xa0000, v202
	global_load_dwordx2 v[148:149], v204, s[18:19]
	global_load_dwordx2 v[150:151], v204, s[18:19] offset:32
	global_load_dwordx2 v[152:153], v204, s[18:19] offset:256
	global_load_dwordx2 v[154:155], v204, s[18:19] offset:288
	s_waitcnt vmcnt(16)
	v_lshlrev_b32_e32 v192, 16, v156
	v_and_b32_e32 v193, 0xffff0000, v156
	v_lshlrev_b32_e32 v194, 16, v157
	v_and_b32_e32 v195, 0xffff0000, v157
	v_pk_fma_f32 v[92:93], v[92:93], 0.5, v[192:193] op_sel_hi:[1,0,1]
	v_pk_fma_f32 v[94:95], v[94:95], 0.5, v[194:195] op_sel_hi:[1,0,1]
	v_lshlrev_b32_e32 v192, 16, v158
	v_and_b32_e32 v193, 0xffff0000, v158
	v_lshlrev_b32_e32 v194, 16, v159
	v_and_b32_e32 v195, 0xffff0000, v159
	v_pk_fma_f32 v[88:89], v[88:89], 0.5, v[192:193] op_sel_hi:[1,0,1]
	v_pk_fma_f32 v[90:91], v[90:91], 0.5, v[194:195] op_sel_hi:[1,0,1]
	v_lshlrev_b32_e32 v192, 16, v160
	v_and_b32_e32 v193, 0xffff0000, v160
	v_lshlrev_b32_e32 v194, 16, v161
	v_and_b32_e32 v195, 0xffff0000, v161
	v_pk_fma_f32 v[84:85], v[84:85], 0.5, v[192:193] op_sel_hi:[1,0,1]
	v_pk_fma_f32 v[86:87], v[86:87], 0.5, v[194:195] op_sel_hi:[1,0,1]
	v_lshlrev_b32_e32 v192, 16, v162
	v_and_b32_e32 v193, 0xffff0000, v162
	v_lshlrev_b32_e32 v194, 16, v163
	v_and_b32_e32 v195, 0xffff0000, v163
	v_pk_fma_f32 v[80:81], v[80:81], 0.5, v[192:193] op_sel_hi:[1,0,1]
	v_pk_fma_f32 v[82:83], v[82:83], 0.5, v[194:195] op_sel_hi:[1,0,1]
	v_mul_f32_e32 v156, v93, v93
	v_mul_f32_e32 v158, v89, v89
	v_mul_f32_e32 v160, v85, v85
	v_mul_f32_e32 v162, v81, v81
	v_mul_f32_e32 v157, v95, v95
	v_mul_f32_e32 v159, v91, v91
	v_mul_f32_e32 v161, v87, v87
	v_mul_f32_e32 v163, v83, v83
	v_fmac_f32_e32 v156, v92, v92
	v_fmac_f32_e32 v158, v88, v88
	v_fmac_f32_e32 v160, v84, v84
	v_fmac_f32_e32 v162, v80, v80
	v_fmac_f32_e32 v157, v94, v94
	v_fmac_f32_e32 v159, v90, v90
	v_fmac_f32_e32 v161, v86, v86
	v_fmac_f32_e32 v163, v82, v82
	v_add_f32_e32 v156, v156, v157
	v_add_f32_e32 v158, v158, v159
	v_add_f32_e32 v160, v160, v161
	v_add_f32_e32 v162, v162, v163
	v_add_f32_e32 v196, v156, v158
	v_add_f32_e32 v196, v196, v160
	v_add_f32_e32 v196, v196, v162
	v_add_u32_e32 v204, 0xb0000, v202
	global_load_dwordx2 v[156:157], v204, s[18:19]
	global_load_dwordx2 v[158:159], v204, s[18:19] offset:32
	global_load_dwordx2 v[160:161], v204, s[18:19] offset:256
	global_load_dwordx2 v[162:163], v204, s[18:19] offset:288
	s_waitcnt vmcnt(16)
	v_lshlrev_b32_e32 v192, 16, v164
	v_and_b32_e32 v193, 0xffff0000, v164
	v_lshlrev_b32_e32 v194, 16, v165
	v_and_b32_e32 v195, 0xffff0000, v165
	v_pk_fma_f32 v[76:77], v[76:77], 0.5, v[192:193] op_sel_hi:[1,0,1]
	v_pk_fma_f32 v[78:79], v[78:79], 0.5, v[194:195] op_sel_hi:[1,0,1]
	v_lshlrev_b32_e32 v192, 16, v176
	v_and_b32_e32 v193, 0xffff0000, v176
	v_lshlrev_b32_e32 v194, 16, v177
	v_and_b32_e32 v195, 0xffff0000, v177
	v_pk_fma_f32 v[72:73], v[72:73], 0.5, v[192:193] op_sel_hi:[1,0,1]
	v_pk_fma_f32 v[74:75], v[74:75], 0.5, v[194:195] op_sel_hi:[1,0,1]
	v_lshlrev_b32_e32 v192, 16, v180
	v_and_b32_e32 v193, 0xffff0000, v180
	v_lshlrev_b32_e32 v194, 16, v181
	v_and_b32_e32 v195, 0xffff0000, v181
	v_pk_fma_f32 v[68:69], v[68:69], 0.5, v[192:193] op_sel_hi:[1,0,1]
	v_pk_fma_f32 v[70:71], v[70:71], 0.5, v[194:195] op_sel_hi:[1,0,1]
	v_lshlrev_b32_e32 v192, 16, v182
	v_and_b32_e32 v193, 0xffff0000, v182
	v_lshlrev_b32_e32 v194, 16, v183
	v_and_b32_e32 v195, 0xffff0000, v183
	v_pk_fma_f32 v[64:65], v[64:65], 0.5, v[192:193] op_sel_hi:[1,0,1]
	v_pk_fma_f32 v[66:67], v[66:67], 0.5, v[194:195] op_sel_hi:[1,0,1]
	v_mul_f32_e32 v164, v77, v77
	v_mul_f32_e32 v176, v73, v73
	v_mul_f32_e32 v180, v69, v69
	v_mul_f32_e32 v182, v65, v65
	v_mul_f32_e32 v165, v79, v79
	v_mul_f32_e32 v177, v75, v75
	v_mul_f32_e32 v181, v71, v71
	v_mul_f32_e32 v183, v67, v67
	v_fmac_f32_e32 v164, v76, v76
	v_fmac_f32_e32 v176, v72, v72
	v_fmac_f32_e32 v180, v68, v68
	v_fmac_f32_e32 v182, v64, v64
	v_fmac_f32_e32 v165, v78, v78
	v_fmac_f32_e32 v177, v74, v74
	v_fmac_f32_e32 v181, v70, v70
	v_fmac_f32_e32 v183, v66, v66
	v_add_f32_e32 v164, v164, v165
	v_add_f32_e32 v176, v176, v177
	v_add_f32_e32 v180, v180, v181
	v_add_f32_e32 v182, v182, v183
	v_add_f32_e32 v197, v164, v176
	v_add_f32_e32 v197, v197, v180
	v_add_f32_e32 v197, v197, v182
	s_waitcnt vmcnt(12)
	v_lshlrev_b32_e32 v192, 16, v184
	v_and_b32_e32 v193, 0xffff0000, v184
	v_lshlrev_b32_e32 v194, 16, v185
	v_and_b32_e32 v195, 0xffff0000, v185
	v_pk_fma_f32 v[60:61], v[60:61], 0.5, v[192:193] op_sel_hi:[1,0,1]
	v_pk_fma_f32 v[62:63], v[62:63], 0.5, v[194:195] op_sel_hi:[1,0,1]
	v_lshlrev_b32_e32 v192, 16, v186
	v_and_b32_e32 v193, 0xffff0000, v186
	v_lshlrev_b32_e32 v194, 16, v187
	v_and_b32_e32 v195, 0xffff0000, v187
	v_pk_fma_f32 v[56:57], v[56:57], 0.5, v[192:193] op_sel_hi:[1,0,1]
	v_pk_fma_f32 v[58:59], v[58:59], 0.5, v[194:195] op_sel_hi:[1,0,1]
	v_lshlrev_b32_e32 v192, 16, v188
	v_and_b32_e32 v193, 0xffff0000, v188
	v_lshlrev_b32_e32 v194, 16, v189
	v_and_b32_e32 v195, 0xffff0000, v189
	v_pk_fma_f32 v[52:53], v[52:53], 0.5, v[192:193] op_sel_hi:[1,0,1]
	v_pk_fma_f32 v[54:55], v[54:55], 0.5, v[194:195] op_sel_hi:[1,0,1]
	v_lshlrev_b32_e32 v192, 16, v190
	v_and_b32_e32 v193, 0xffff0000, v190
	v_lshlrev_b32_e32 v194, 16, v191
	v_and_b32_e32 v195, 0xffff0000, v191
	v_pk_fma_f32 v[48:49], v[48:49], 0.5, v[192:193] op_sel_hi:[1,0,1]
	v_pk_fma_f32 v[50:51], v[50:51], 0.5, v[194:195] op_sel_hi:[1,0,1]
	v_mul_f32_e32 v184, v61, v61
	v_mul_f32_e32 v186, v57, v57
	v_mul_f32_e32 v188, v53, v53
	v_mul_f32_e32 v190, v49, v49
	v_mul_f32_e32 v185, v63, v63
	v_mul_f32_e32 v187, v59, v59
	v_mul_f32_e32 v189, v55, v55
	v_mul_f32_e32 v191, v51, v51
	v_fmac_f32_e32 v184, v60, v60
	v_fmac_f32_e32 v186, v56, v56
	v_fmac_f32_e32 v188, v52, v52
	v_fmac_f32_e32 v190, v48, v48
	v_fmac_f32_e32 v185, v62, v62
	v_fmac_f32_e32 v187, v58, v58
	v_fmac_f32_e32 v189, v54, v54
	v_fmac_f32_e32 v191, v50, v50
	v_add_f32_e32 v184, v184, v185
	v_add_f32_e32 v186, v186, v187
	v_add_f32_e32 v188, v188, v189
	v_add_f32_e32 v190, v190, v191
	v_add_f32_e32 v198, v184, v186
	v_add_f32_e32 v198, v198, v188
	v_add_f32_e32 v198, v198, v190
	s_waitcnt vmcnt(8)
	v_lshlrev_b32_e32 v192, 16, v140
	v_and_b32_e32 v193, 0xffff0000, v140
	v_lshlrev_b32_e32 v194, 16, v141
	v_and_b32_e32 v195, 0xffff0000, v141
	v_pk_fma_f32 v[44:45], v[44:45], 0.5, v[192:193] op_sel_hi:[1,0,1]
	v_pk_fma_f32 v[46:47], v[46:47], 0.5, v[194:195] op_sel_hi:[1,0,1]
	v_lshlrev_b32_e32 v192, 16, v142
	v_and_b32_e32 v193, 0xffff0000, v142
	v_lshlrev_b32_e32 v194, 16, v143
	v_and_b32_e32 v195, 0xffff0000, v143
	v_pk_fma_f32 v[40:41], v[40:41], 0.5, v[192:193] op_sel_hi:[1,0,1]
	v_pk_fma_f32 v[42:43], v[42:43], 0.5, v[194:195] op_sel_hi:[1,0,1]
	v_lshlrev_b32_e32 v192, 16, v144
	v_and_b32_e32 v193, 0xffff0000, v144
	v_lshlrev_b32_e32 v194, 16, v145
	v_and_b32_e32 v195, 0xffff0000, v145
	v_pk_fma_f32 v[36:37], v[36:37], 0.5, v[192:193] op_sel_hi:[1,0,1]
	v_pk_fma_f32 v[38:39], v[38:39], 0.5, v[194:195] op_sel_hi:[1,0,1]
	v_lshlrev_b32_e32 v192, 16, v146
	v_and_b32_e32 v193, 0xffff0000, v146
	v_lshlrev_b32_e32 v194, 16, v147
	v_and_b32_e32 v195, 0xffff0000, v147
	v_pk_fma_f32 v[32:33], v[32:33], 0.5, v[192:193] op_sel_hi:[1,0,1]
	v_pk_fma_f32 v[34:35], v[34:35], 0.5, v[194:195] op_sel_hi:[1,0,1]
	v_mul_f32_e32 v140, v45, v45
	v_mul_f32_e32 v142, v41, v41
	v_mul_f32_e32 v144, v37, v37
	v_mul_f32_e32 v146, v33, v33
	v_mul_f32_e32 v141, v47, v47
	v_mul_f32_e32 v143, v43, v43
	v_mul_f32_e32 v145, v39, v39
	v_mul_f32_e32 v147, v35, v35
	v_fmac_f32_e32 v140, v44, v44
	v_fmac_f32_e32 v142, v40, v40
	v_fmac_f32_e32 v144, v36, v36
	v_fmac_f32_e32 v146, v32, v32
	v_fmac_f32_e32 v141, v46, v46
	v_fmac_f32_e32 v143, v42, v42
	v_fmac_f32_e32 v145, v38, v38
	v_fmac_f32_e32 v147, v34, v34
	v_add_f32_e32 v140, v140, v141
	v_add_f32_e32 v142, v142, v143
	v_add_f32_e32 v144, v144, v145
	v_add_f32_e32 v146, v146, v147
	v_add_f32_e32 v199, v140, v142
	v_add_f32_e32 v199, v199, v144
	v_add_f32_e32 v199, v199, v146
	s_waitcnt vmcnt(4)
	v_lshlrev_b32_e32 v192, 16, v148
	v_and_b32_e32 v193, 0xffff0000, v148
	v_lshlrev_b32_e32 v194, 16, v149
	v_and_b32_e32 v195, 0xffff0000, v149
	v_pk_fma_f32 v[28:29], v[28:29], 0.5, v[192:193] op_sel_hi:[1,0,1]
	v_pk_fma_f32 v[30:31], v[30:31], 0.5, v[194:195] op_sel_hi:[1,0,1]
	v_lshlrev_b32_e32 v192, 16, v150
	v_and_b32_e32 v193, 0xffff0000, v150
	v_lshlrev_b32_e32 v194, 16, v151
	v_and_b32_e32 v195, 0xffff0000, v151
	v_pk_fma_f32 v[24:25], v[24:25], 0.5, v[192:193] op_sel_hi:[1,0,1]
	v_pk_fma_f32 v[26:27], v[26:27], 0.5, v[194:195] op_sel_hi:[1,0,1]
	v_lshlrev_b32_e32 v192, 16, v152
	v_and_b32_e32 v193, 0xffff0000, v152
	v_lshlrev_b32_e32 v194, 16, v153
	v_and_b32_e32 v195, 0xffff0000, v153
	v_pk_fma_f32 v[20:21], v[20:21], 0.5, v[192:193] op_sel_hi:[1,0,1]
	v_pk_fma_f32 v[22:23], v[22:23], 0.5, v[194:195] op_sel_hi:[1,0,1]
	v_lshlrev_b32_e32 v192, 16, v154
	v_and_b32_e32 v193, 0xffff0000, v154
	v_lshlrev_b32_e32 v194, 16, v155
	v_and_b32_e32 v195, 0xffff0000, v155
	v_pk_fma_f32 v[16:17], v[16:17], 0.5, v[192:193] op_sel_hi:[1,0,1]
	v_pk_fma_f32 v[18:19], v[18:19], 0.5, v[194:195] op_sel_hi:[1,0,1]
	v_mul_f32_e32 v148, v29, v29
	v_mul_f32_e32 v150, v25, v25
	v_mul_f32_e32 v152, v21, v21
	v_mul_f32_e32 v154, v17, v17
	v_mul_f32_e32 v149, v31, v31
	v_mul_f32_e32 v151, v27, v27
	v_mul_f32_e32 v153, v23, v23
	v_mul_f32_e32 v155, v19, v19
	v_fmac_f32_e32 v148, v28, v28
	v_fmac_f32_e32 v150, v24, v24
	v_fmac_f32_e32 v152, v20, v20
	v_fmac_f32_e32 v154, v16, v16
	v_fmac_f32_e32 v149, v30, v30
	v_fmac_f32_e32 v151, v26, v26
	v_fmac_f32_e32 v153, v22, v22
	v_fmac_f32_e32 v155, v18, v18
	v_add_f32_e32 v148, v148, v149
	v_add_f32_e32 v150, v150, v151
	v_add_f32_e32 v152, v152, v153
	v_add_f32_e32 v154, v154, v155
	v_add_f32_e32 v200, v148, v150
	v_add_f32_e32 v200, v200, v152
	v_add_f32_e32 v200, v200, v154
	s_waitcnt vmcnt(0)
	v_lshlrev_b32_e32 v192, 16, v156
	v_and_b32_e32 v193, 0xffff0000, v156
	v_lshlrev_b32_e32 v194, 16, v157
	v_and_b32_e32 v195, 0xffff0000, v157
	v_pk_fma_f32 v[12:13], v[12:13], 0.5, v[192:193] op_sel_hi:[1,0,1]
	v_pk_fma_f32 v[14:15], v[14:15], 0.5, v[194:195] op_sel_hi:[1,0,1]
	v_lshlrev_b32_e32 v192, 16, v158
	v_and_b32_e32 v193, 0xffff0000, v158
	v_lshlrev_b32_e32 v194, 16, v159
	v_and_b32_e32 v195, 0xffff0000, v159
	v_pk_fma_f32 v[8:9], v[8:9], 0.5, v[192:193] op_sel_hi:[1,0,1]
	v_pk_fma_f32 v[10:11], v[10:11], 0.5, v[194:195] op_sel_hi:[1,0,1]
	v_lshlrev_b32_e32 v192, 16, v160
	v_and_b32_e32 v193, 0xffff0000, v160
	v_lshlrev_b32_e32 v194, 16, v161
	v_and_b32_e32 v195, 0xffff0000, v161
	v_pk_fma_f32 v[4:5], v[4:5], 0.5, v[192:193] op_sel_hi:[1,0,1]
	v_pk_fma_f32 v[6:7], v[6:7], 0.5, v[194:195] op_sel_hi:[1,0,1]
	v_lshlrev_b32_e32 v192, 16, v162
	v_and_b32_e32 v193, 0xffff0000, v162
	v_lshlrev_b32_e32 v194, 16, v163
	v_and_b32_e32 v195, 0xffff0000, v163
	v_pk_fma_f32 v[0:1], v[0:1], 0.5, v[192:193] op_sel_hi:[1,0,1]
	v_pk_fma_f32 v[2:3], v[2:3], 0.5, v[194:195] op_sel_hi:[1,0,1]
	v_mul_f32_e32 v156, v13, v13
	v_mul_f32_e32 v158, v9, v9
	v_mul_f32_e32 v160, v5, v5
	v_mul_f32_e32 v162, v1, v1
	v_mul_f32_e32 v157, v15, v15
	v_mul_f32_e32 v159, v11, v11
	v_mul_f32_e32 v161, v7, v7
	v_mul_f32_e32 v163, v3, v3
	v_fmac_f32_e32 v156, v12, v12
	v_fmac_f32_e32 v158, v8, v8
	v_fmac_f32_e32 v160, v4, v4
	v_fmac_f32_e32 v162, v0, v0
	v_fmac_f32_e32 v157, v14, v14
	v_fmac_f32_e32 v159, v10, v10
	v_fmac_f32_e32 v161, v6, v6
	v_fmac_f32_e32 v163, v2, v2
	v_add_f32_e32 v156, v156, v157
	v_add_f32_e32 v158, v158, v159
	v_add_f32_e32 v160, v160, v161
	v_add_f32_e32 v162, v162, v163
	v_add_f32_e32 v201, v156, v158
	v_add_f32_e32 v201, v201, v160
	v_add_f32_e32 v201, v201, v162
	ds_bpermute_b32 v140, v207, v167
	ds_bpermute_b32 v141, v207, v175
	ds_bpermute_b32 v142, v207, v196
	ds_bpermute_b32 v143, v207, v197
	ds_bpermute_b32 v144, v207, v198
	ds_bpermute_b32 v145, v207, v199
	ds_bpermute_b32 v146, v207, v200
	ds_bpermute_b32 v147, v207, v201
	s_waitcnt lgkmcnt(0)
	v_add_f32_e32 v167, v167, v140
	v_add_f32_e32 v175, v175, v141
	v_add_f32_e32 v196, v196, v142
	v_add_f32_e32 v197, v197, v143
	v_add_f32_e32 v198, v198, v144
	v_add_f32_e32 v199, v199, v145
	v_add_f32_e32 v200, v200, v146
	v_add_f32_e32 v201, v201, v147
	ds_bpermute_b32 v140, v208, v167
	ds_bpermute_b32 v141, v208, v175
	ds_bpermute_b32 v142, v208, v196
	ds_bpermute_b32 v143, v208, v197
	ds_bpermute_b32 v144, v208, v198
	ds_bpermute_b32 v145, v208, v199
	ds_bpermute_b32 v146, v208, v200
	ds_bpermute_b32 v147, v208, v201
	s_waitcnt lgkmcnt(0)
	v_add_f32_e32 v167, v167, v140
	v_add_f32_e32 v175, v175, v141
	v_add_f32_e32 v196, v196, v142
	v_add_f32_e32 v197, v197, v143
	v_add_f32_e32 v198, v198, v144
	v_add_f32_e32 v199, v199, v145
	v_add_f32_e32 v200, v200, v146
	v_add_f32_e32 v201, v201, v147
	v_cmp_gt_u32_e32 vcc, 16, v206
	s_and_saveexec_b64 s[22:23], vcc
	global_atomic_add_f32 v205, v167, s[8:9]
	global_atomic_add_f32 v205, v175, s[8:9] offset:64
	global_atomic_add_f32 v205, v196, s[8:9] offset:128
	global_atomic_add_f32 v205, v197, s[8:9] offset:192
	global_atomic_add_f32 v205, v198, s[8:9] offset:512
	global_atomic_add_f32 v205, v199, s[8:9] offset:576
	global_atomic_add_f32 v205, v200, s[8:9] offset:640
	global_atomic_add_f32 v205, v201, s[8:9] offset:704
	s_mov_b64 exec, s[22:23]
	s_waitcnt vmcnt(0)
	s_waitcnt lgkmcnt(0)
	s_barrier
	s_and_saveexec_b64 s[22:23], s[82:83]
	s_cbranch_execz .LBB0_1071
	s_lshl_b32 s24, s45, 6
	s_mov_b64 s[26:27], exec
	s_ashr_i32 s25, s24, 31
	s_lshl_b64 s[24:25], s[24:25], 2
	buffer_wbl2 sc1
	s_waitcnt vmcnt(0)
	s_waitcnt vmcnt(0)
	v_mbcnt_lo_u32_b32 v166, s26, 0
	s_add_u32 s24, s36, s24
	v_mbcnt_hi_u32_b32 v166, s27, v166
	s_addc_u32 s25, s37, s25
	v_cmp_eq_u32_e32 vcc, 0, v166
	s_and_saveexec_b64 s[28:29], vcc
	s_cbranch_execz .LBB0_1062
	s_bcnt1_i32_b64 s26, s[26:27]
	v_mov_b32_e32 v166, s26
	global_atomic_add v129, v166, s[24:25]

.LBB0_1071:
	s_or_b64 exec, exec, s[22:23]
	s_barrier
	v_readlane_b32 s24, v253, 61
	v_readlane_b32 s25, v253, 62
	v_readlane_b32 s26, v253, 63
	v_readlane_b32 s27, v254, 0
	global_load_dword v156, v205, s[8:9] sc1
	global_load_dword v157, v205, s[8:9] offset:64 sc1
	global_load_dword v158, v205, s[8:9] offset:128 sc1
	global_load_dword v159, v205, s[8:9] offset:192 sc1
	global_load_dword v160, v205, s[8:9] offset:512 sc1
	global_load_dword v161, v205, s[8:9] offset:576 sc1
	global_load_dword v162, v205, s[8:9] offset:640 sc1
	global_load_dword v163, v205, s[8:9] offset:704 sc1
	v_lshl_or_b32 v204, s46, 8, v170
	v_lshlrev_b32_e32 v207, 2, v204
	global_load_dwordx4 v[140:143], v207, s[54:55]
	global_load_dwordx4 v[144:147], v207, s[54:55] offset:64
	global_load_dwordx4 v[148:151], v207, s[54:55] offset:512
	global_load_dwordx4 v[152:155], v207, s[54:55] offset:576
	v_lshlrev_b32_e32 v206, 1, v203
	s_waitcnt vmcnt(0)
	v_fmamk_f32 v156, v156, 0x3a000000, v174
	v_fmamk_f32 v157, v157, 0x3a000000, v174
	v_fmamk_f32 v158, v158, 0x3a000000, v174
	v_fmamk_f32 v159, v159, 0x3a000000, v174
	v_fmamk_f32 v160, v160, 0x3a000000, v174
	v_fmamk_f32 v161, v161, 0x3a000000, v174
	v_fmamk_f32 v162, v162, 0x3a000000, v174
	v_fmamk_f32 v163, v163, 0x3a000000, v174
	v_rsq_f32_e32 v156, v156
	v_rsq_f32_e32 v157, v157
	v_rsq_f32_e32 v158, v158
	v_rsq_f32_e32 v159, v159
	v_rsq_f32_e32 v160, v160
	v_rsq_f32_e32 v161, v161
	v_rsq_f32_e32 v162, v162
	v_rsq_f32_e32 v163, v163
	v_pk_mul_f32 v[124:125], v[124:125], v[156:157] op_sel_hi:[1,0]
	v_pk_mul_f32 v[126:127], v[126:127], v[156:157] op_sel_hi:[1,0]
	v_pk_mul_f32 v[120:121], v[120:121], v[156:157] op_sel_hi:[1,0]
	v_pk_mul_f32 v[122:123], v[122:123], v[156:157] op_sel_hi:[1,0]
	v_pk_mul_f32 v[116:117], v[116:117], v[156:157] op_sel_hi:[1,0]
	v_pk_mul_f32 v[118:119], v[118:119], v[156:157] op_sel_hi:[1,0]
	v_pk_mul_f32 v[112:113], v[112:113], v[156:157] op_sel_hi:[1,0]
	v_pk_mul_f32 v[114:115], v[114:115], v[156:157] op_sel_hi:[1,0]
	v_pk_mul_f32 v[124:125], v[140:141], v[124:125]
	v_pk_mul_f32 v[126:127], v[142:143], v[126:127]
	v_pk_mul_f32 v[120:121], v[144:145], v[120:121]
	v_pk_mul_f32 v[122:123], v[146:147], v[122:123]
	v_pk_mul_f32 v[116:117], v[148:149], v[116:117]
	v_pk_mul_f32 v[118:119], v[150:151], v[118:119]
	v_pk_mul_f32 v[112:113], v[152:153], v[112:113]
	v_pk_mul_f32 v[114:115], v[154:155], v[114:115]
	v_mov_b32_e32 v204, v206
	global_store_dwordx4 v204, v[124:127], s[24:25]
	global_store_dwordx4 v204, v[120:123], s[24:25] offset:64
	global_store_dwordx4 v204, v[116:119], s[24:25] offset:512
	global_store_dwordx4 v204, v[112:115], s[24:25] offset:576
	v_pk_mul_f32 v[108:109], v[108:109], v[156:157] op_sel:[0,1] op_sel_hi:[1,1]
	v_pk_mul_f32 v[110:111], v[110:111], v[156:157] op_sel:[0,1] op_sel_hi:[1,1]
	v_pk_mul_f32 v[104:105], v[104:105], v[156:157] op_sel:[0,1] op_sel_hi:[1,1]
	v_pk_mul_f32 v[106:107], v[106:107], v[156:157] op_sel:[0,1] op_sel_hi:[1,1]
	v_pk_mul_f32 v[100:101], v[100:101], v[156:157] op_sel:[0,1] op_sel_hi:[1,1]
	v_pk_mul_f32 v[102:103], v[102:103], v[156:157] op_sel:[0,1] op_sel_hi:[1,1]
	v_pk_mul_f32 v[96:97], v[96:97], v[156:157] op_sel:[0,1] op_sel_hi:[1,1]
	v_pk_mul_f32 v[98:99], v[98:99], v[156:157] op_sel:[0,1] op_sel_hi:[1,1]
	v_pk_mul_f32 v[108:109], v[140:141], v[108:109]
	v_pk_mul_f32 v[110:111], v[142:143], v[110:111]
	v_pk_mul_f32 v[104:105], v[144:145], v[104:105]
	v_pk_mul_f32 v[106:107], v[146:147], v[106:107]
	v_pk_mul_f32 v[100:101], v[148:149], v[100:101]
	v_pk_mul_f32 v[102:103], v[150:151], v[102:103]
	v_pk_mul_f32 v[96:97], v[152:153], v[96:97]
	v_pk_mul_f32 v[98:99], v[154:155], v[98:99]
	v_add_u32_e32 v204, 0x20000, v206
	global_store_dwordx4 v204, v[108:111], s[24:25]
	global_store_dwordx4 v204, v[104:107], s[24:25] offset:64
	global_store_dwordx4 v204, v[100:103], s[24:25] offset:512
	global_store_dwordx4 v204, v[96:99], s[24:25] offset:576
	v_pk_mul_f32 v[92:93], v[92:93], v[158:159] op_sel_hi:[1,0]
	v_pk_mul_f32 v[94:95], v[94:95], v[158:159] op_sel_hi:[1,0]
	v_pk_mul_f32 v[88:89], v[88:89], v[158:159] op_sel_hi:[1,0]
	v_pk_mul_f32 v[90:91], v[90:91], v[158:159] op_sel_hi:[1,0]
	v_pk_mul_f32 v[84:85], v[84:85], v[158:159] op_sel_hi:[1,0]
	v_pk_mul_f32 v[86:87], v[86:87], v[158:159] op_sel_hi:[1,0]
	v_pk_mul_f32 v[80:81], v[80:81], v[158:159] op_sel_hi:[1,0]
	v_pk_mul_f32 v[82:83], v[82:83], v[158:159] op_sel_hi:[1,0]
	v_pk_mul_f32 v[92:93], v[140:141], v[92:93]
	v_pk_mul_f32 v[94:95], v[142:143], v[94:95]
	v_pk_mul_f32 v[88:89], v[144:145], v[88:89]
	v_pk_mul_f32 v[90:91], v[146:147], v[90:91]
	v_pk_mul_f32 v[84:85], v[148:149], v[84:85]
	v_pk_mul_f32 v[86:87], v[150:151], v[86:87]
	v_pk_mul_f32 v[80:81], v[152:153], v[80:81]
	v_pk_mul_f32 v[82:83], v[154:155], v[82:83]
	v_add_u32_e32 v204, 0x40000, v206
	global_store_dwordx4 v204, v[92:95], s[24:25]
	global_store_dwordx4 v204, v[88:91], s[24:25] offset:64
	global_store_dwordx4 v204, v[84:87], s[24:25] offset:512
	global_store_dwordx4 v204, v[80:83], s[24:25] offset:576
	v_pk_mul_f32 v[76:77], v[76:77], v[158:159] op_sel:[0,1] op_sel_hi:[1,1]
	v_pk_mul_f32 v[78:79], v[78:79], v[158:159] op_sel:[0,1] op_sel_hi:[1,1]
	v_pk_mul_f32 v[72:73], v[72:73], v[158:159] op_sel:[0,1] op_sel_hi:[1,1]
	v_pk_mul_f32 v[74:75], v[74:75], v[158:159] op_sel:[0,1] op_sel_hi:[1,1]
	v_pk_mul_f32 v[68:69], v[68:69], v[158:159] op_sel:[0,1] op_sel_hi:[1,1]
	v_pk_mul_f32 v[70:71], v[70:71], v[158:159] op_sel:[0,1] op_sel_hi:[1,1]
	v_pk_mul_f32 v[64:65], v[64:65], v[158:159] op_sel:[0,1] op_sel_hi:[1,1]
	v_pk_mul_f32 v[66:67], v[66:67], v[158:159] op_sel:[0,1] op_sel_hi:[1,1]
	v_pk_mul_f32 v[76:77], v[140:141], v[76:77]
	v_pk_mul_f32 v[78:79], v[142:143], v[78:79]
	v_pk_mul_f32 v[72:73], v[144:145], v[72:73]
	v_pk_mul_f32 v[74:75], v[146:147], v[74:75]
	v_pk_mul_f32 v[68:69], v[148:149], v[68:69]
	v_pk_mul_f32 v[70:71], v[150:151], v[70:71]
	v_pk_mul_f32 v[64:65], v[152:153], v[64:65]
	v_pk_mul_f32 v[66:67], v[154:155], v[66:67]
	v_add_u32_e32 v204, 0x60000, v206
	global_store_dwordx4 v204, v[76:79], s[24:25]
	global_store_dwordx4 v204, v[72:75], s[24:25] offset:64
	global_store_dwordx4 v204, v[68:71], s[24:25] offset:512
	global_store_dwordx4 v204, v[64:67], s[24:25] offset:576
	v_pk_mul_f32 v[60:61], v[60:61], v[160:161] op_sel_hi:[1,0]
	v_pk_mul_f32 v[62:63], v[62:63], v[160:161] op_sel_hi:[1,0]
	v_pk_mul_f32 v[56:57], v[56:57], v[160:161] op_sel_hi:[1,0]
	v_pk_mul_f32 v[58:59], v[58:59], v[160:161] op_sel_hi:[1,0]
	v_pk_mul_f32 v[52:53], v[52:53], v[160:161] op_sel_hi:[1,0]
	v_pk_mul_f32 v[54:55], v[54:55], v[160:161] op_sel_hi:[1,0]
	v_pk_mul_f32 v[48:49], v[48:49], v[160:161] op_sel_hi:[1,0]
	v_pk_mul_f32 v[50:51], v[50:51], v[160:161] op_sel_hi:[1,0]
	v_pk_mul_f32 v[60:61], v[140:141], v[60:61]
	v_pk_mul_f32 v[62:63], v[142:143], v[62:63]
	v_pk_mul_f32 v[56:57], v[144:145], v[56:57]
	v_pk_mul_f32 v[58:59], v[146:147], v[58:59]
	v_pk_mul_f32 v[52:53], v[148:149], v[52:53]
	v_pk_mul_f32 v[54:55], v[150:151], v[54:55]
	v_pk_mul_f32 v[48:49], v[152:153], v[48:49]
	v_pk_mul_f32 v[50:51], v[154:155], v[50:51]
	v_add_u32_e32 v204, 0x100000, v206
	global_store_dwordx4 v204, v[60:63], s[24:25]
	global_store_dwordx4 v204, v[56:59], s[24:25] offset:64
	global_store_dwordx4 v204, v[52:55], s[24:25] offset:512
	global_store_dwordx4 v204, v[48:51], s[24:25] offset:576
	v_pk_mul_f32 v[44:45], v[44:45], v[160:161] op_sel:[0,1] op_sel_hi:[1,1]
	v_pk_mul_f32 v[46:47], v[46:47], v[160:161] op_sel:[0,1] op_sel_hi:[1,1]
	v_pk_mul_f32 v[40:41], v[40:41], v[160:161] op_sel:[0,1] op_sel_hi:[1,1]
	v_pk_mul_f32 v[42:43], v[42:43], v[160:161] op_sel:[0,1] op_sel_hi:[1,1]
	v_pk_mul_f32 v[36:37], v[36:37], v[160:161] op_sel:[0,1] op_sel_hi:[1,1]
	v_pk_mul_f32 v[38:39], v[38:39], v[160:161] op_sel:[0,1] op_sel_hi:[1,1]
	v_pk_mul_f32 v[32:33], v[32:33], v[160:161] op_sel:[0,1] op_sel_hi:[1,1]
	v_pk_mul_f32 v[34:35], v[34:35], v[160:161] op_sel:[0,1] op_sel_hi:[1,1]
	v_pk_mul_f32 v[44:45], v[140:141], v[44:45]
	v_pk_mul_f32 v[46:47], v[142:143], v[46:47]
	v_pk_mul_f32 v[40:41], v[144:145], v[40:41]
	v_pk_mul_f32 v[42:43], v[146:147], v[42:43]
	v_pk_mul_f32 v[36:37], v[148:149], v[36:37]
	v_pk_mul_f32 v[38:39], v[150:151], v[38:39]
	v_pk_mul_f32 v[32:33], v[152:153], v[32:33]
	v_pk_mul_f32 v[34:35], v[154:155], v[34:35]
	v_add_u32_e32 v204, 0x120000, v206
	global_store_dwordx4 v204, v[44:47], s[24:25]
	global_store_dwordx4 v204, v[40:43], s[24:25] offset:64
	global_store_dwordx4 v204, v[36:39], s[24:25] offset:512
	global_store_dwordx4 v204, v[32:35], s[24:25] offset:576
	v_pk_mul_f32 v[28:29], v[28:29], v[162:163] op_sel_hi:[1,0]
	v_pk_mul_f32 v[30:31], v[30:31], v[162:163] op_sel_hi:[1,0]
	v_pk_mul_f32 v[24:25], v[24:25], v[162:163] op_sel_hi:[1,0]
	v_pk_mul_f32 v[26:27], v[26:27], v[162:163] op_sel_hi:[1,0]
	v_pk_mul_f32 v[20:21], v[20:21], v[162:163] op_sel_hi:[1,0]
	v_pk_mul_f32 v[22:23], v[22:23], v[162:163] op_sel_hi:[1,0]
	v_pk_mul_f32 v[16:17], v[16:17], v[162:163] op_sel_hi:[1,0]
	v_pk_mul_f32 v[18:19], v[18:19], v[162:163] op_sel_hi:[1,0]
	v_pk_mul_f32 v[28:29], v[140:141], v[28:29]
	v_pk_mul_f32 v[30:31], v[142:143], v[30:31]
	v_pk_mul_f32 v[24:25], v[144:145], v[24:25]
	v_pk_mul_f32 v[26:27], v[146:147], v[26:27]
	v_pk_mul_f32 v[20:21], v[148:149], v[20:21]
	v_pk_mul_f32 v[22:23], v[150:151], v[22:23]
	v_pk_mul_f32 v[16:17], v[152:153], v[16:17]
	v_pk_mul_f32 v[18:19], v[154:155], v[18:19]
	v_add_u32_e32 v204, 0x140000, v206
	global_store_dwordx4 v204, v[28:31], s[24:25]
	global_store_dwordx4 v204, v[24:27], s[24:25] offset:64
	global_store_dwordx4 v204, v[20:23], s[24:25] offset:512
	global_store_dwordx4 v204, v[16:19], s[24:25] offset:576
	v_pk_mul_f32 v[12:13], v[12:13], v[162:163] op_sel:[0,1] op_sel_hi:[1,1]
	v_pk_mul_f32 v[14:15], v[14:15], v[162:163] op_sel:[0,1] op_sel_hi:[1,1]
	v_pk_mul_f32 v[8:9], v[8:9], v[162:163] op_sel:[0,1] op_sel_hi:[1,1]
	v_pk_mul_f32 v[10:11], v[10:11], v[162:163] op_sel:[0,1] op_sel_hi:[1,1]
	v_pk_mul_f32 v[4:5], v[4:5], v[162:163] op_sel:[0,1] op_sel_hi:[1,1]
	v_pk_mul_f32 v[6:7], v[6:7], v[162:163] op_sel:[0,1] op_sel_hi:[1,1]
	v_pk_mul_f32 v[0:1], v[0:1], v[162:163] op_sel:[0,1] op_sel_hi:[1,1]
	v_pk_mul_f32 v[2:3], v[2:3], v[162:163] op_sel:[0,1] op_sel_hi:[1,1]
	v_pk_mul_f32 v[12:13], v[140:141], v[12:13]
	v_pk_mul_f32 v[14:15], v[142:143], v[14:15]
	v_pk_mul_f32 v[8:9], v[144:145], v[8:9]
	v_pk_mul_f32 v[10:11], v[146:147], v[10:11]
	v_pk_mul_f32 v[4:5], v[148:149], v[4:5]
	v_pk_mul_f32 v[6:7], v[150:151], v[6:7]
	v_pk_mul_f32 v[0:1], v[152:153], v[0:1]
	v_pk_mul_f32 v[2:3], v[154:155], v[2:3]
	v_add_u32_e32 v204, 0x160000, v206
	global_store_dwordx4 v204, v[12:15], s[24:25]
	global_store_dwordx4 v204, v[8:11], s[24:25] offset:64
	global_store_dwordx4 v204, v[4:7], s[24:25] offset:512
	s_and_b64 vcc, exec, s[4:5]
	s_mov_b64 s[4:5], -1
	global_store_dwordx4 v204, v[0:3], s[24:25] offset:576
	s_cbranch_vccnz .LBB0_1028
	s_andn2_b64 vcc, exec, s[2:3]
	s_cbranch_vccnz .LBB0_1027
	s_barrier
	s_branch .LBB0_1027
